# MF=2 DMA GEMM loops: first MFMAs of the previous step issued right after the barrier, before the DMA issue and the fragment reads (MFMA pipe fed from the first cycle)
# baseline (speedup 1.0000x reference)
; #define MFMA32(a, b, c) __builtin_amdgcn_mfma_f32_32x32x16_bf16((a), (b), (c), 0, 0, 0)
; template <int MF, int BK, class Epi>
; DI void gemm_phase_t(char* lds, const GemmDesc g, const Epi epi) {
;     ...
;     for (int kt = 0; kt < nk; ++kt) {
;       __syncthreads();
;       const u16* sA = sbase + (kt & 1) * STG;
;       const u16* sB = sA + BM * LS;
;       if (kt + 1 < nk) {
;         u16* nA = sbase + ((kt + 1) & 1) * STG;
; #pragma unroll
;         for (int j = 0; j < APT; ++j) *(u32x4*)(nA + (lr + RSTEP * j) * LS + lc * 8) = ra[j];
; #pragma unroll
;         for (int j = 0; j < BPT; ++j) *(u32x4*)(nA + BM * LS + (lr + RSTEP * j) * LS + lc * 8) = rb[j];
;         if (kt + 2 < nk) {
; #pragma unroll
;           for (int j = 0; j < APT; ++j) ra[j] = *(const u32x4*)(Ap + (size_t)j * RSTEP * g.lda + (kt + 2) * BK);
; #pragma unroll
;           for (int j = 0; j < BPT; ++j) rb[j] = *(const u32x4*)(Bp + (size_t)j * RSTEP * g.ldb + (kt + 2) * BK);
;         }
;       }
;       bf16x8 af[NKK][MF], bfr[NKK][2];
; #pragma unroll
;       for (int kk = 0; kk < NKK; ++kk) {
; #pragma unroll
;         for (int ni = 0; ni < 2; ++ni) bfr[kk][ni] = *(const bf16x8*)(sB + (wn * 64 + ni * 32 + l31) * LS + kk * 16 + h * 8);
; #pragma unroll
;         for (int mi = 0; mi < MF; ++mi) af[kk][mi] = *(const bf16x8*)(sA + (wm * (MF * 32) + mi * 32 + l31) * LS + kk * 16 + h * 8);
;       }
;       __builtin_amdgcn_sched_barrier(0);
; #pragma unroll
;       for (int kk = 0; kk < NKK; ++kk)
; #pragma unroll
;         for (int mi = 0; mi < MF; ++mi)
; #pragma unroll
;           for (int ni = 0; ni < 2; ++ni) acc[mi][ni] = MFMA32(bfr[kk][ni], af[kk][mi], acc[mi][ni]);
.Ldma_dn_loop:
	s_waitcnt vmcnt(0)
	s_waitcnt lgkmcnt(0)
	s_barrier
	v_mfma_f32_32x32x16_bf16 v[52:67], v[68:71], v[76:79], v[52:67]
	s_add_i32 m0, s100, 0x0
	s_nop 0
	global_load_lds_dwordx4 v108, s[12:13]
	s_add_i32 m0, s100, 0x1000
	s_nop 0
	global_load_lds_dwordx4 v109, s[12:13]
	s_add_i32 m0, s100, 0x2000
	s_nop 0
	global_load_lds_dwordx4 v110, s[12:13]
	s_add_i32 m0, s100, 0x3000
	s_nop 0
	global_load_lds_dwordx4 v111, s[12:13]
	s_add_i32 m0, s100, 0x4000
	s_nop 0
	global_load_lds_dwordx4 v108, s[14:15]
	s_add_i32 m0, s100, 0x5000
	s_nop 0
	global_load_lds_dwordx4 v109, s[14:15]
	s_add_i32 m0, s100, 0x6000
	s_nop 0
	global_load_lds_dwordx4 v110, s[14:15]
	s_add_i32 m0, s100, 0x7000
	s_nop 0
	global_load_lds_dwordx4 v111, s[14:15]
	s_add_u32 s12, s12, 0x80
	s_addc_u32 s13, s13, 0
	s_add_u32 s14, s14, 0x80
	s_addc_u32 s15, s15, 0
	v_mfma_f32_32x32x16_bf16 v[36:51], v[72:75], v[76:79], v[36:51]
	ds_read_b128 v[150:153], v234 offset:32768
	ds_read_b128 v[154:157], v234 offset:36864
	ds_read_b128 v[158:161], v114 offset:32768
	ds_read_b128 v[162:165], v114 offset:36864
	ds_read_b128 v[168:171], v235 offset:32768
	ds_read_b128 v[172:175], v235 offset:36864
	ds_read_b128 v[176:179], v115 offset:32768
	ds_read_b128 v[180:183], v115 offset:36864
	v_mfma_f32_32x32x16_bf16 v[20:35], v[68:71], v[80:83], v[20:35]
	ds_read_b128 v[184:187], v236 offset:32768
	ds_read_b128 v[188:191], v236 offset:36864
	ds_read_b128 v[192:195], v116 offset:32768
	ds_read_b128 v[198:201], v116 offset:36864
	ds_read_b128 v[218:221], v237 offset:32768
	ds_read_b128 v[222:225], v237 offset:36864
	ds_read_b128 v[226:229], v117 offset:32768
	ds_read_b128 v[230:233], v117 offset:36864
	v_mfma_f32_32x32x16_bf16 v[4:19], v[72:75], v[80:83], v[4:19]
	v_mfma_f32_32x32x16_bf16 v[52:67], v[84:87], v[92:95], v[52:67]
	v_mfma_f32_32x32x16_bf16 v[36:51], v[88:91], v[92:95], v[36:51]
	v_mfma_f32_32x32x16_bf16 v[20:35], v[84:87], v[96:99], v[20:35]
	v_mfma_f32_32x32x16_bf16 v[4:19], v[88:91], v[96:99], v[4:19]
	v_mfma_f32_32x32x16_bf16 v[52:67], v[118:121], v[126:129], v[52:67]
	v_mfma_f32_32x32x16_bf16 v[36:51], v[122:125], v[126:129], v[36:51]
	v_mfma_f32_32x32x16_bf16 v[20:35], v[118:121], v[130:133], v[20:35]
	v_mfma_f32_32x32x16_bf16 v[4:19], v[122:125], v[130:133], v[4:19]
	v_mfma_f32_32x32x16_bf16 v[52:67], v[134:137], v[142:145], v[52:67]
	v_mfma_f32_32x32x16_bf16 v[36:51], v[138:141], v[142:145], v[36:51]
	v_mfma_f32_32x32x16_bf16 v[20:35], v[134:137], v[146:149], v[20:35]
	v_mfma_f32_32x32x16_bf16 v[4:19], v[138:141], v[146:149], v[4:19]
	s_waitcnt vmcnt(0)
	s_waitcnt lgkmcnt(0)
	s_barrier
	v_mfma_f32_32x32x16_bf16 v[52:67], v[150:153], v[158:161], v[52:67]
	s_add_i32 m0, s100, 0x8000
	s_nop 0
	global_load_lds_dwordx4 v108, s[12:13]
	s_add_i32 m0, s100, 0x9000
	s_nop 0
	global_load_lds_dwordx4 v109, s[12:13]
	s_add_i32 m0, s100, 0xa000
	s_nop 0
	global_load_lds_dwordx4 v110, s[12:13]
	s_add_i32 m0, s100, 0xb000
	s_nop 0
	global_load_lds_dwordx4 v111, s[12:13]
	s_add_i32 m0, s100, 0xc000
	s_nop 0
	global_load_lds_dwordx4 v108, s[14:15]
	s_add_i32 m0, s100, 0xd000
	s_nop 0
	global_load_lds_dwordx4 v109, s[14:15]
	s_add_i32 m0, s100, 0xe000
	s_nop 0
	global_load_lds_dwordx4 v110, s[14:15]
	s_add_i32 m0, s100, 0xf000
	s_nop 0
	global_load_lds_dwordx4 v111, s[14:15]
	s_add_u32 s12, s12, 0x80
	s_addc_u32 s13, s13, 0
	s_add_u32 s14, s14, 0x80
	s_addc_u32 s15, s15, 0
	v_mfma_f32_32x32x16_bf16 v[36:51], v[154:157], v[158:161], v[36:51]
	ds_read_b128 v[68:71], v234
	ds_read_b128 v[72:75], v234 offset:4096
	ds_read_b128 v[76:79], v114
	ds_read_b128 v[80:83], v114 offset:4096
	ds_read_b128 v[84:87], v235
	ds_read_b128 v[88:91], v235 offset:4096
	ds_read_b128 v[92:95], v115
	ds_read_b128 v[96:99], v115 offset:4096
	v_mfma_f32_32x32x16_bf16 v[20:35], v[150:153], v[162:165], v[20:35]
	ds_read_b128 v[118:121], v236
	ds_read_b128 v[122:125], v236 offset:4096
	ds_read_b128 v[126:129], v116
	ds_read_b128 v[130:133], v116 offset:4096
	ds_read_b128 v[134:137], v237
	ds_read_b128 v[138:141], v237 offset:4096
	ds_read_b128 v[142:145], v117
	ds_read_b128 v[146:149], v117 offset:4096
	v_mfma_f32_32x32x16_bf16 v[4:19], v[154:157], v[162:165], v[4:19]
	v_mfma_f32_32x32x16_bf16 v[52:67], v[168:171], v[176:179], v[52:67]
	v_mfma_f32_32x32x16_bf16 v[36:51], v[172:175], v[176:179], v[36:51]
	v_mfma_f32_32x32x16_bf16 v[20:35], v[168:171], v[180:183], v[20:35]
	v_mfma_f32_32x32x16_bf16 v[4:19], v[172:175], v[180:183], v[4:19]
	v_mfma_f32_32x32x16_bf16 v[52:67], v[184:187], v[192:195], v[52:67]
	v_mfma_f32_32x32x16_bf16 v[36:51], v[188:191], v[192:195], v[36:51]
	v_mfma_f32_32x32x16_bf16 v[20:35], v[184:187], v[198:201], v[20:35]
	v_mfma_f32_32x32x16_bf16 v[4:19], v[188:191], v[198:201], v[4:19]
	v_mfma_f32_32x32x16_bf16 v[52:67], v[218:221], v[226:229], v[52:67]
	v_mfma_f32_32x32x16_bf16 v[36:51], v[222:225], v[226:229], v[36:51]
	v_mfma_f32_32x32x16_bf16 v[20:35], v[218:221], v[230:233], v[20:35]
	v_mfma_f32_32x32x16_bf16 v[4:19], v[222:225], v[230:233], v[4:19]
	s_add_i32 s9, s9, -1
	s_cmp_lg_u32 s9, 0
	s_cbranch_scc1 .Ldma_dn_loop
	s_waitcnt vmcnt(0)
	s_waitcnt lgkmcnt(0)
	s_barrier
; #define MFMA32(a, b, c) __builtin_amdgcn_mfma_f32_32x32x16_bf16((a), (b), (c), 0, 0, 0)
; template <int MF, int BK, class Epi>
; DI void gemm_phase_t(char* lds, const GemmDesc g, const Epi epi) {
;     ...
;       for (int kk = 0; kk < NKK; ++kk) {
; #pragma unroll
;         for (int ni = 0; ni < 2; ++ni) bfr[kk][ni] = *(const bf16x8*)(sB + (wn * 64 + ni * 32 + l31) * LS + kk * 16 + h * 8);
; #pragma unroll
;         for (int mi = 0; mi < MF; ++mi) af[kk][mi] = *(const bf16x8*)(sA + (wm * (MF * 32) + mi * 32 + l31) * LS + kk * 16 + h * 8);
;       }
;       __builtin_amdgcn_sched_barrier(0);
; #pragma unroll
;       for (int kk = 0; kk < NKK; ++kk)
; #pragma unroll
;         for (int mi = 0; mi < MF; ++mi)
; #pragma unroll
;           for (int ni = 0; ni < 2; ++ni) acc[mi][ni] = MFMA32(bfr[kk][ni], af[kk][mi], acc[mi][ni]);
;   template <int MF> DI void operator()(f32x16 (&acc)[MF][2], int mb, int nb, int l31, int h) const {
; #pragma unroll
;     for (int mi = 0; mi < MF; ++mi) {
;       const int row = mb + mi * 32 + l31;
;       const float* gr = gate + (size_t)modrow(row) * 6144;
;       const float* rp = row < TL ? res_lat + (size_t)row * D : res_ctx + (size_t)(row - TL) * D;
;       float* op = row < TL ? out_lat + (size_t)row * D : out_ctx + (size_t)(row - TL) * D;
; #pragma unroll
;       for (int g4 = 0; g4 < 4; ++g4)
; #pragma unroll
;         for (int ni = 0; ni < 2; ++ni) {
;           const int col0 = nb + 16 * g4 + 8 * h + 4 * ni;
;           const float4 gt = *(const float4*)(gr + col0);
;           const float4 rv = *(const float4*)(rp + col0);
;           *(float4*)(op + col0) = make_float4(rv.x + gt.x * acc[mi][ni][4 * g4], rv.y + gt.y * acc[mi][ni][4 * g4 + 1], rv.z + gt.z * acc[mi][ni][4 * g4 + 2], rv.w + gt.w * acc[mi][ni][4 * g4 + 3]);
	v_mfma_f32_32x32x16_bf16 v[52:67], v[68:71], v[76:79], v[52:67]
	v_mfma_f32_32x32x16_bf16 v[36:51], v[72:75], v[76:79], v[36:51]
	ds_read_b128 v[150:153], v234 offset:32768
	ds_read_b128 v[154:157], v234 offset:36864
	ds_read_b128 v[158:161], v114 offset:32768
	ds_read_b128 v[162:165], v114 offset:36864
	ds_read_b128 v[168:171], v235 offset:32768
	ds_read_b128 v[172:175], v235 offset:36864
	ds_read_b128 v[176:179], v115 offset:32768
	ds_read_b128 v[180:183], v115 offset:36864
	v_mfma_f32_32x32x16_bf16 v[20:35], v[68:71], v[80:83], v[20:35]
	ds_read_b128 v[184:187], v236 offset:32768
	ds_read_b128 v[188:191], v236 offset:36864
	ds_read_b128 v[192:195], v116 offset:32768
	ds_read_b128 v[198:201], v116 offset:36864
	ds_read_b128 v[218:221], v237 offset:32768
	ds_read_b128 v[222:225], v237 offset:36864
	ds_read_b128 v[226:229], v117 offset:32768
	ds_read_b128 v[230:233], v117 offset:36864
	v_mfma_f32_32x32x16_bf16 v[4:19], v[72:75], v[80:83], v[4:19]
	v_mfma_f32_32x32x16_bf16 v[52:67], v[84:87], v[92:95], v[52:67]
	v_mfma_f32_32x32x16_bf16 v[36:51], v[88:91], v[92:95], v[36:51]
	v_mfma_f32_32x32x16_bf16 v[20:35], v[84:87], v[96:99], v[20:35]
	v_mfma_f32_32x32x16_bf16 v[4:19], v[88:91], v[96:99], v[4:19]
	v_mfma_f32_32x32x16_bf16 v[52:67], v[118:121], v[126:129], v[52:67]
	v_mfma_f32_32x32x16_bf16 v[36:51], v[122:125], v[126:129], v[36:51]
	v_mfma_f32_32x32x16_bf16 v[20:35], v[118:121], v[130:133], v[20:35]
	v_mfma_f32_32x32x16_bf16 v[4:19], v[122:125], v[130:133], v[4:19]
	v_mfma_f32_32x32x16_bf16 v[52:67], v[134:137], v[142:145], v[52:67]
	v_mfma_f32_32x32x16_bf16 v[36:51], v[138:141], v[142:145], v[36:51]
	v_mfma_f32_32x32x16_bf16 v[20:35], v[134:137], v[146:149], v[20:35]
	v_mfma_f32_32x32x16_bf16 v[4:19], v[138:141], v[146:149], v[4:19]
	s_waitcnt lgkmcnt(0)
	v_mfma_f32_32x32x16_bf16 v[52:67], v[150:153], v[158:161], v[52:67]
	v_mfma_f32_32x32x16_bf16 v[36:51], v[154:157], v[158:161], v[36:51]
	v_mfma_f32_32x32x16_bf16 v[20:35], v[150:153], v[162:165], v[20:35]
	v_mfma_f32_32x32x16_bf16 v[4:19], v[154:157], v[162:165], v[4:19]
	v_mfma_f32_32x32x16_bf16 v[52:67], v[168:171], v[176:179], v[52:67]
	v_mfma_f32_32x32x16_bf16 v[36:51], v[172:175], v[176:179], v[36:51]
	v_mfma_f32_32x32x16_bf16 v[20:35], v[168:171], v[180:183], v[20:35]
	v_mfma_f32_32x32x16_bf16 v[4:19], v[172:175], v[180:183], v[4:19]
	v_mfma_f32_32x32x16_bf16 v[52:67], v[184:187], v[192:195], v[52:67]
	v_mfma_f32_32x32x16_bf16 v[36:51], v[188:191], v[192:195], v[36:51]
	v_mfma_f32_32x32x16_bf16 v[20:35], v[184:187], v[198:201], v[20:35]
	v_mfma_f32_32x32x16_bf16 v[4:19], v[188:191], v[198:201], v[4:19]
	v_mfma_f32_32x32x16_bf16 v[52:67], v[218:221], v[226:229], v[52:67]
	v_mfma_f32_32x32x16_bf16 v[36:51], v[222:225], v[226:229], v[36:51]
	v_mfma_f32_32x32x16_bf16 v[20:35], v[218:221], v[230:233], v[20:35]
	v_mfma_f32_32x32x16_bf16 v[4:19], v[222:225], v[230:233], v[4:19]
	v_or_b32_e32 v68, s8, v113
	v_readlane_b32 s8, v252, 40
	s_add_i32 s6, s6, s8
	s_cmpk_gt_i32 s6, 0x7ff
	v_readlane_b32 s9, v252, 41
	v_mov_b32_e32 v88, s21
	v_mov_b32_e32 v89, s22
	v_mov_b32_e32 v90, s20
	v_add_u32_e32 v86, s7, v112
	v_min_i32_e32 v69, 0x8000, v86
	v_ashrrev_i32_e32 v69, 12, v69
	s_mov_b32 s7, 0x8000
	v_mul_hi_i32_i24_e32 v71, 0x6000, v69
	v_mul_i32_i24_e32 v70, 0x6000, v69
	v_cmp_gt_i32_e32 vcc, s7, v86
	v_add_u32_e32 v69, 0xffff8000, v86
	v_ashrrev_i32_e32 v72, 31, v86
	v_cndmask_b32_e32 v73, 0, v72, vcc
	v_cndmask_b32_e32 v72, v69, v86, vcc
	v_mov_b32_e32 v87, s23
	v_ashrrev_i32_e32 v69, 31, v68
	v_lshl_add_u64 v[70:71], s[2:3], 0, v[70:71]
	v_cndmask_b32_e32 v75, v87, v88, vcc
	v_cndmask_b32_e32 v74, v89, v90, vcc
	v_lshlrev_b64 v[72:73], 12, v[72:73]
	v_lshlrev_b64 v[68:69], 2, v[68:69]
	v_lshl_add_u64 v[72:73], v[74:75], 0, v[72:73]
	v_lshl_add_u64 v[84:85], v[72:73], 0, v[68:69]
	s_movk_i32 s7, 0x7fe0
	v_cmp_gt_i32_e32 vcc, s7, v86
	v_lshl_add_u64 v[82:83], v[70:71], 0, v[68:69]
	s_movk_i32 s7, 0x7fe0
	v_cmp_gt_i32_e32 vcc, s7, v86
	v_or_b32_e32 v76, 32, v86
	v_ashrrev_i32_e32 v72, 31, v76
	v_add_u32_e32 v74, 0xffff8020, v86
	v_cndmask_b32_e32 v73, 0, v72, vcc
	v_cndmask_b32_e32 v72, v74, v76, vcc
	v_cndmask_b32_e32 v75, v87, v88, vcc
	v_cndmask_b32_e32 v74, v89, v90, vcc
	v_lshlrev_b64 v[72:73], 12, v[72:73]
	v_lshl_add_u64 v[72:73], v[74:75], 0, v[72:73]
	v_lshl_add_u64 v[80:81], v[72:73], 0, v[68:69]
	global_load_dwordx4 v[118:121], v[82:83], off
	global_load_dwordx4 v[150:153], v[84:85], off
	global_load_dwordx4 v[122:125], v[82:83], off offset:16
	global_load_dwordx4 v[154:157], v[84:85], off offset:16
	global_load_dwordx4 v[126:129], v[82:83], off offset:64
	global_load_dwordx4 v[158:161], v[84:85], off offset:64
	global_load_dwordx4 v[130:133], v[82:83], off offset:80
	global_load_dwordx4 v[162:165], v[84:85], off offset:80
	global_load_dwordx4 v[134:137], v[82:83], off offset:128
	global_load_dwordx4 v[168:171], v[84:85], off offset:128
	global_load_dwordx4 v[138:141], v[82:83], off offset:144
	global_load_dwordx4 v[172:175], v[84:85], off offset:144
	global_load_dwordx4 v[142:145], v[82:83], off offset:192
	global_load_dwordx4 v[176:179], v[84:85], off offset:192
	global_load_dwordx4 v[146:149], v[82:83], off offset:208
	global_load_dwordx4 v[180:183], v[84:85], off offset:208
	global_load_dwordx4 v[184:187], v[80:81], off
	global_load_dwordx4 v[188:191], v[80:81], off offset:16
	global_load_dwordx4 v[192:195], v[80:81], off offset:64
	global_load_dwordx4 v[198:201], v[80:81], off offset:80
	global_load_dwordx4 v[218:221], v[80:81], off offset:128
	global_load_dwordx4 v[222:225], v[80:81], off offset:144
	global_load_dwordx4 v[226:229], v[80:81], off offset:192
	global_load_dwordx4 v[230:233], v[80:81], off offset:208
	s_waitcnt vmcnt(8)
;   template <int MF> DI void operator()(f32x16 (&acc)[MF][2], int mb, int nb, int l31, int h) const {
; #pragma unroll
;     for (int mi = 0; mi < MF; ++mi) {
;       const int row = mb + mi * 32 + l31;
;       const float* gr = gate + (size_t)modrow(row) * 6144;
;       const float* rp = row < TL ? res_lat + (size_t)row * D : res_ctx + (size_t)(row - TL) * D;
;       float* op = row < TL ? out_lat + (size_t)row * D : out_ctx + (size_t)(row - TL) * D;
; #pragma unroll
;       for (int g4 = 0; g4 < 4; ++g4)
; #pragma unroll
;         for (int ni = 0; ni < 2; ++ni) {
;           const int col0 = nb + 16 * g4 + 8 * h + 4 * ni;
;           const float4 gt = *(const float4*)(gr + col0);
;           const float4 rv = *(const float4*)(rp + col0);
;           *(float4*)(op + col0) = make_float4(rv.x + gt.x * acc[mi][ni][4 * g4], rv.y + gt.y * acc[mi][ni][4 * g4 + 1], rv.z + gt.z * acc[mi][ni][4 * g4 + 2], rv.w + gt.w * acc[mi][ni][4 * g4 + 3]);
;         }
;     }
	s_nop 4
	v_fma_f32 v52, v52, v118, v150
	v_fma_f32 v53, v53, v119, v151
	v_fma_f32 v54, v54, v120, v152
	v_fma_f32 v55, v55, v121, v153
	global_store_dwordx4 v[84:85], v[52:55], off
	v_fma_f32 v36, v36, v122, v154
	v_fma_f32 v37, v37, v123, v155
	v_fma_f32 v38, v38, v124, v156
	v_fma_f32 v39, v39, v125, v157
	global_store_dwordx4 v[84:85], v[36:39], off offset:16
	v_fma_f32 v56, v56, v126, v158
	v_fma_f32 v57, v57, v127, v159
	v_fma_f32 v58, v58, v128, v160
	v_fma_f32 v59, v59, v129, v161
	global_store_dwordx4 v[84:85], v[56:59], off offset:64
	v_fma_f32 v40, v40, v130, v162
	v_fma_f32 v41, v41, v131, v163
	v_fma_f32 v42, v42, v132, v164
	v_fma_f32 v43, v43, v133, v165
	global_store_dwordx4 v[84:85], v[40:43], off offset:80
	v_fma_f32 v60, v60, v134, v168
	v_fma_f32 v61, v61, v135, v169
	v_fma_f32 v62, v62, v136, v170
	v_fma_f32 v63, v63, v137, v171
	global_store_dwordx4 v[84:85], v[60:63], off offset:128
	v_fma_f32 v44, v44, v138, v172
	v_fma_f32 v45, v45, v139, v173
	v_fma_f32 v46, v46, v140, v174
	v_fma_f32 v47, v47, v141, v175
	global_store_dwordx4 v[84:85], v[44:47], off offset:144
	v_fma_f32 v64, v64, v142, v176
	v_fma_f32 v65, v65, v143, v177
	v_fma_f32 v66, v66, v144, v178
	v_fma_f32 v67, v67, v145, v179
	global_store_dwordx4 v[84:85], v[64:67], off offset:192
	v_fma_f32 v48, v48, v146, v180
	v_fma_f32 v49, v49, v147, v181
	v_fma_f32 v50, v50, v148, v182
	v_fma_f32 v51, v51, v149, v183
	global_store_dwordx4 v[84:85], v[48:51], off offset:208
	s_waitcnt vmcnt(8)
	v_fma_f32 v20, v20, v118, v184
	v_fma_f32 v21, v21, v119, v185
	v_fma_f32 v22, v22, v120, v186
	v_fma_f32 v23, v23, v121, v187
	global_store_dwordx4 v[80:81], v[20:23], off
	v_fma_f32 v4, v4, v122, v188
	v_fma_f32 v5, v5, v123, v189
	v_fma_f32 v6, v6, v124, v190
	v_fma_f32 v7, v7, v125, v191
	global_store_dwordx4 v[80:81], v[4:7], off offset:16
	v_fma_f32 v24, v24, v126, v192
	v_fma_f32 v25, v25, v127, v193
	v_fma_f32 v26, v26, v128, v194
	v_fma_f32 v27, v27, v129, v195
	global_store_dwordx4 v[80:81], v[24:27], off offset:64
	v_fma_f32 v8, v8, v130, v198
	v_fma_f32 v9, v9, v131, v199
	v_fma_f32 v10, v10, v132, v200
	v_fma_f32 v11, v11, v133, v201
	global_store_dwordx4 v[80:81], v[8:11], off offset:80
	v_fma_f32 v28, v28, v134, v218
	v_fma_f32 v29, v29, v135, v219
	v_fma_f32 v30, v30, v136, v220
	v_fma_f32 v31, v31, v137, v221
	global_store_dwordx4 v[80:81], v[28:31], off offset:128
	v_fma_f32 v12, v12, v138, v222
	v_fma_f32 v13, v13, v139, v223
	v_fma_f32 v14, v14, v140, v224
	v_fma_f32 v15, v15, v141, v225
	global_store_dwordx4 v[80:81], v[12:15], off offset:144
	v_fma_f32 v32, v32, v142, v226
	v_fma_f32 v33, v33, v143, v227
	v_fma_f32 v34, v34, v144, v228
	v_fma_f32 v35, v35, v145, v229
	global_store_dwordx4 v[80:81], v[32:35], off offset:192
	v_fma_f32 v16, v16, v146, v230
	v_fma_f32 v17, v17, v147, v231
	v_fma_f32 v18, v18, v148, v232
	v_fma_f32 v19, v19, v149, v233
	global_store_dwordx4 v[80:81], v[16:19], off offset:208
	s_cbranch_scc0 .LBB0_34

; #define MFMA32(a, b, c) __builtin_amdgcn_mfma_f32_32x32x16_bf16((a), (b), (c), 0, 0, 0)
; template <int MF, int BK, class Epi>
; DI void gemm_phase_t(char* lds, const GemmDesc g, const Epi epi) {
;     ...
;     for (int kt = 0; kt < nk; ++kt) {
;       __syncthreads();
;       const u16* sA = sbase + (kt & 1) * STG;
;       const u16* sB = sA + BM * LS;
;       if (kt + 1 < nk) {
;         u16* nA = sbase + ((kt + 1) & 1) * STG;
; #pragma unroll
;         for (int j = 0; j < APT; ++j) *(u32x4*)(nA + (lr + RSTEP * j) * LS + lc * 8) = ra[j];
; #pragma unroll
;         for (int j = 0; j < BPT; ++j) *(u32x4*)(nA + BM * LS + (lr + RSTEP * j) * LS + lc * 8) = rb[j];
;         if (kt + 2 < nk) {
; #pragma unroll
;           for (int j = 0; j < APT; ++j) ra[j] = *(const u32x4*)(Ap + (size_t)j * RSTEP * g.lda + (kt + 2) * BK);
; #pragma unroll
;           for (int j = 0; j < BPT; ++j) rb[j] = *(const u32x4*)(Bp + (size_t)j * RSTEP * g.ldb + (kt + 2) * BK);
;         }
;       }
;       bf16x8 af[NKK][MF], bfr[NKK][2];
; #pragma unroll
;       for (int kk = 0; kk < NKK; ++kk) {
; #pragma unroll
;         for (int ni = 0; ni < 2; ++ni) bfr[kk][ni] = *(const bf16x8*)(sB + (wn * 64 + ni * 32 + l31) * LS + kk * 16 + h * 8);
; #pragma unroll
;         for (int mi = 0; mi < MF; ++mi) af[kk][mi] = *(const bf16x8*)(sA + (wm * (MF * 32) + mi * 32 + l31) * LS + kk * 16 + h * 8);
;       }
;       __builtin_amdgcn_sched_barrier(0);
; #pragma unroll
;       for (int kk = 0; kk < NKK; ++kk)
; #pragma unroll
;         for (int mi = 0; mi < MF; ++mi)
; #pragma unroll
;           for (int ni = 0; ni < 2; ++ni) acc[mi][ni] = MFMA32(bfr[kk][ni], af[kk][mi], acc[mi][ni]);
.Ldma_op_loop:
	s_waitcnt vmcnt(0)
	s_waitcnt lgkmcnt(0)
	s_barrier
	v_mfma_f32_32x32x16_bf16 v[52:67], v[68:71], v[76:79], v[52:67]
	s_add_i32 m0, s100, 0x0
	s_nop 0
	global_load_lds_dwordx4 v108, s[12:13]
	s_add_i32 m0, s100, 0x1000
	s_nop 0
	global_load_lds_dwordx4 v109, s[12:13]
	s_add_i32 m0, s100, 0x2000
	s_nop 0
	global_load_lds_dwordx4 v110, s[12:13]
	s_add_i32 m0, s100, 0x3000
	s_nop 0
	global_load_lds_dwordx4 v111, s[12:13]
	s_add_i32 m0, s100, 0x4000
	s_nop 0
	global_load_lds_dwordx4 v108, s[14:15]
	s_add_i32 m0, s100, 0x5000
	s_nop 0
	global_load_lds_dwordx4 v109, s[14:15]
	s_add_i32 m0, s100, 0x6000
	s_nop 0
	global_load_lds_dwordx4 v110, s[14:15]
	s_add_i32 m0, s100, 0x7000
	s_nop 0
	global_load_lds_dwordx4 v111, s[14:15]
	s_add_u32 s12, s12, 0x80
	s_addc_u32 s13, s13, 0
	s_add_u32 s14, s14, 0x80
	s_addc_u32 s15, s15, 0
	v_mfma_f32_32x32x16_bf16 v[36:51], v[72:75], v[76:79], v[36:51]
	ds_read_b128 v[150:153], v234 offset:32768
	ds_read_b128 v[154:157], v234 offset:36864
	ds_read_b128 v[158:161], v238 offset:32768
	ds_read_b128 v[162:165], v238 offset:36864
	ds_read_b128 v[168:171], v235 offset:32768
	ds_read_b128 v[172:175], v235 offset:36864
	ds_read_b128 v[176:179], v239 offset:32768
	ds_read_b128 v[180:183], v239 offset:36864
	v_mfma_f32_32x32x16_bf16 v[20:35], v[68:71], v[80:83], v[20:35]
	ds_read_b128 v[184:187], v236 offset:32768
	ds_read_b128 v[188:191], v236 offset:36864
	ds_read_b128 v[192:195], v240 offset:32768
	ds_read_b128 v[198:201], v240 offset:36864
	ds_read_b128 v[218:221], v237 offset:32768
	ds_read_b128 v[222:225], v237 offset:36864
	ds_read_b128 v[226:229], v241 offset:32768
	ds_read_b128 v[230:233], v241 offset:36864
	v_mfma_f32_32x32x16_bf16 v[4:19], v[72:75], v[80:83], v[4:19]
	v_mfma_f32_32x32x16_bf16 v[52:67], v[84:87], v[92:95], v[52:67]
	v_mfma_f32_32x32x16_bf16 v[36:51], v[88:91], v[92:95], v[36:51]
	v_mfma_f32_32x32x16_bf16 v[20:35], v[84:87], v[96:99], v[20:35]
	v_mfma_f32_32x32x16_bf16 v[4:19], v[88:91], v[96:99], v[4:19]
	v_mfma_f32_32x32x16_bf16 v[52:67], v[118:121], v[126:129], v[52:67]
	v_mfma_f32_32x32x16_bf16 v[36:51], v[122:125], v[126:129], v[36:51]
	v_mfma_f32_32x32x16_bf16 v[20:35], v[118:121], v[130:133], v[20:35]
	v_mfma_f32_32x32x16_bf16 v[4:19], v[122:125], v[130:133], v[4:19]
	v_mfma_f32_32x32x16_bf16 v[52:67], v[134:137], v[142:145], v[52:67]
	v_mfma_f32_32x32x16_bf16 v[36:51], v[138:141], v[142:145], v[36:51]
	v_mfma_f32_32x32x16_bf16 v[20:35], v[134:137], v[146:149], v[20:35]
	v_mfma_f32_32x32x16_bf16 v[4:19], v[138:141], v[146:149], v[4:19]
	s_waitcnt vmcnt(0)
	s_waitcnt lgkmcnt(0)
	s_barrier
	v_mfma_f32_32x32x16_bf16 v[52:67], v[150:153], v[158:161], v[52:67]
	s_add_i32 m0, s100, 0x8000
	s_nop 0
	global_load_lds_dwordx4 v108, s[12:13]
	s_add_i32 m0, s100, 0x9000
	s_nop 0
	global_load_lds_dwordx4 v109, s[12:13]
	s_add_i32 m0, s100, 0xa000
	s_nop 0
	global_load_lds_dwordx4 v110, s[12:13]
	s_add_i32 m0, s100, 0xb000
	s_nop 0
	global_load_lds_dwordx4 v111, s[12:13]
	s_add_i32 m0, s100, 0xc000
	s_nop 0
	global_load_lds_dwordx4 v108, s[14:15]
	s_add_i32 m0, s100, 0xd000
	s_nop 0
	global_load_lds_dwordx4 v109, s[14:15]
	s_add_i32 m0, s100, 0xe000
	s_nop 0
	global_load_lds_dwordx4 v110, s[14:15]
	s_add_i32 m0, s100, 0xf000
	s_nop 0
	global_load_lds_dwordx4 v111, s[14:15]
	s_add_u32 s12, s12, 0x80
	s_addc_u32 s13, s13, 0
	s_add_u32 s14, s14, 0x80
	s_addc_u32 s15, s15, 0
	v_mfma_f32_32x32x16_bf16 v[36:51], v[154:157], v[158:161], v[36:51]
	ds_read_b128 v[68:71], v234
	ds_read_b128 v[72:75], v234 offset:4096
	ds_read_b128 v[76:79], v238
	ds_read_b128 v[80:83], v238 offset:4096
	ds_read_b128 v[84:87], v235
	ds_read_b128 v[88:91], v235 offset:4096
	ds_read_b128 v[92:95], v239
	ds_read_b128 v[96:99], v239 offset:4096
	v_mfma_f32_32x32x16_bf16 v[20:35], v[150:153], v[162:165], v[20:35]
	ds_read_b128 v[118:121], v236
	ds_read_b128 v[122:125], v236 offset:4096
	ds_read_b128 v[126:129], v240
	ds_read_b128 v[130:133], v240 offset:4096
	ds_read_b128 v[134:137], v237
	ds_read_b128 v[138:141], v237 offset:4096
	ds_read_b128 v[142:145], v241
	ds_read_b128 v[146:149], v241 offset:4096
	v_mfma_f32_32x32x16_bf16 v[4:19], v[154:157], v[162:165], v[4:19]
	v_mfma_f32_32x32x16_bf16 v[52:67], v[168:171], v[176:179], v[52:67]
	v_mfma_f32_32x32x16_bf16 v[36:51], v[172:175], v[176:179], v[36:51]
	v_mfma_f32_32x32x16_bf16 v[20:35], v[168:171], v[180:183], v[20:35]
	v_mfma_f32_32x32x16_bf16 v[4:19], v[172:175], v[180:183], v[4:19]
	v_mfma_f32_32x32x16_bf16 v[52:67], v[184:187], v[192:195], v[52:67]
	v_mfma_f32_32x32x16_bf16 v[36:51], v[188:191], v[192:195], v[36:51]
	v_mfma_f32_32x32x16_bf16 v[20:35], v[184:187], v[198:201], v[20:35]
	v_mfma_f32_32x32x16_bf16 v[4:19], v[188:191], v[198:201], v[4:19]
	v_mfma_f32_32x32x16_bf16 v[52:67], v[218:221], v[226:229], v[52:67]
	v_mfma_f32_32x32x16_bf16 v[36:51], v[222:225], v[226:229], v[36:51]
	v_mfma_f32_32x32x16_bf16 v[20:35], v[218:221], v[230:233], v[20:35]
	v_mfma_f32_32x32x16_bf16 v[4:19], v[222:225], v[230:233], v[4:19]
	s_add_i32 s9, s9, -1
	s_cmp_lg_u32 s9, 0
	s_cbranch_scc1 .Ldma_op_loop
	s_waitcnt vmcnt(0)
	s_waitcnt lgkmcnt(0)
	s_barrier
; #define MFMA32(a, b, c) __builtin_amdgcn_mfma_f32_32x32x16_bf16((a), (b), (c), 0, 0, 0)
; template <int MF, int BK, class Epi>
; DI void gemm_phase_t(char* lds, const GemmDesc g, const Epi epi) {
;     ...
;       __builtin_amdgcn_sched_barrier(0);
; #pragma unroll
;       for (int kk = 0; kk < NKK; ++kk)
; #pragma unroll
;         for (int mi = 0; mi < MF; ++mi)
; #pragma unroll
;           for (int ni = 0; ni < 2; ++ni) acc[mi][ni] = MFMA32(bfr[kk][ni], af[kk][mi], acc[mi][ni]);
;     }
;     epi(acc, g.mbase + m0 + wm * (MF * 32), n0 + wn * 64, l31, h);
;   template <int MF> DI void operator()(f32x16 (&acc)[MF][2], int mb, int nb, int l31, int h) const {
; #pragma unroll
;     for (int mi = 0; mi < MF; ++mi) {
;       const int row = mb + mi * 32 + l31;
;       const float* gr = gate + (size_t)modrow(row) * 6144;
;       const float* rp = row < TL ? res_lat + (size_t)row * D : res_ctx + (size_t)(row - TL) * D;
;       float* op = row < TL ? out_lat + (size_t)row * D : out_ctx + (size_t)(row - TL) * D;
; #pragma unroll
;       for (int g4 = 0; g4 < 4; ++g4)
; #pragma unroll
;         for (int ni = 0; ni < 2; ++ni) {
;           const int col0 = nb + 16 * g4 + 8 * h + 4 * ni;
;           const float4 gt = *(const float4*)(gr + col0);
;           const float4 rv = *(const float4*)(rp + col0);
;           *(float4*)(op + col0) = make_float4(rv.x + gt.x * acc[mi][ni][4 * g4], rv.y + gt.y * acc[mi][ni][4 * g4 + 1], rv.z + gt.z * acc[mi][ni][4 * g4 + 2], rv.w + gt.w * acc[mi][ni][4 * g4 + 3]);
;         }
	v_mfma_f32_32x32x16_bf16 v[52:67], v[68:71], v[76:79], v[52:67]
	v_mfma_f32_32x32x16_bf16 v[36:51], v[72:75], v[76:79], v[36:51]
	ds_read_b128 v[150:153], v234 offset:32768
	ds_read_b128 v[154:157], v234 offset:36864
	ds_read_b128 v[158:161], v238 offset:32768
	ds_read_b128 v[162:165], v238 offset:36864
	ds_read_b128 v[168:171], v235 offset:32768
	ds_read_b128 v[172:175], v235 offset:36864
	ds_read_b128 v[176:179], v239 offset:32768
	ds_read_b128 v[180:183], v239 offset:36864
	v_mfma_f32_32x32x16_bf16 v[20:35], v[68:71], v[80:83], v[20:35]
	ds_read_b128 v[184:187], v236 offset:32768
	ds_read_b128 v[188:191], v236 offset:36864
	ds_read_b128 v[192:195], v240 offset:32768
	ds_read_b128 v[198:201], v240 offset:36864
	ds_read_b128 v[218:221], v237 offset:32768
	ds_read_b128 v[222:225], v237 offset:36864
	ds_read_b128 v[226:229], v241 offset:32768
	ds_read_b128 v[230:233], v241 offset:36864
	v_mfma_f32_32x32x16_bf16 v[4:19], v[72:75], v[80:83], v[4:19]
	v_mfma_f32_32x32x16_bf16 v[52:67], v[84:87], v[92:95], v[52:67]
	v_mfma_f32_32x32x16_bf16 v[36:51], v[88:91], v[92:95], v[36:51]
	v_mfma_f32_32x32x16_bf16 v[20:35], v[84:87], v[96:99], v[20:35]
	v_mfma_f32_32x32x16_bf16 v[4:19], v[88:91], v[96:99], v[4:19]
	v_mfma_f32_32x32x16_bf16 v[52:67], v[118:121], v[126:129], v[52:67]
	v_mfma_f32_32x32x16_bf16 v[36:51], v[122:125], v[126:129], v[36:51]
	v_mfma_f32_32x32x16_bf16 v[20:35], v[118:121], v[130:133], v[20:35]
	v_mfma_f32_32x32x16_bf16 v[4:19], v[122:125], v[130:133], v[4:19]
	v_mfma_f32_32x32x16_bf16 v[52:67], v[134:137], v[142:145], v[52:67]
	v_mfma_f32_32x32x16_bf16 v[36:51], v[138:141], v[142:145], v[36:51]
	v_mfma_f32_32x32x16_bf16 v[20:35], v[134:137], v[146:149], v[20:35]
	v_mfma_f32_32x32x16_bf16 v[4:19], v[138:141], v[146:149], v[4:19]
	s_waitcnt lgkmcnt(0)
	v_mfma_f32_32x32x16_bf16 v[52:67], v[150:153], v[158:161], v[52:67]
	v_mfma_f32_32x32x16_bf16 v[36:51], v[154:157], v[158:161], v[36:51]
	v_mfma_f32_32x32x16_bf16 v[20:35], v[150:153], v[162:165], v[20:35]
	v_mfma_f32_32x32x16_bf16 v[4:19], v[154:157], v[162:165], v[4:19]
	v_mfma_f32_32x32x16_bf16 v[52:67], v[168:171], v[176:179], v[52:67]
	v_mfma_f32_32x32x16_bf16 v[36:51], v[172:175], v[176:179], v[36:51]
	v_mfma_f32_32x32x16_bf16 v[20:35], v[168:171], v[180:183], v[20:35]
	v_mfma_f32_32x32x16_bf16 v[4:19], v[172:175], v[180:183], v[4:19]
	v_mfma_f32_32x32x16_bf16 v[52:67], v[184:187], v[192:195], v[52:67]
	v_mfma_f32_32x32x16_bf16 v[36:51], v[188:191], v[192:195], v[36:51]
	v_mfma_f32_32x32x16_bf16 v[20:35], v[184:187], v[198:201], v[20:35]
	v_mfma_f32_32x32x16_bf16 v[4:19], v[188:191], v[198:201], v[4:19]
	v_mfma_f32_32x32x16_bf16 v[52:67], v[218:221], v[226:229], v[52:67]
	v_mfma_f32_32x32x16_bf16 v[36:51], v[222:225], v[226:229], v[36:51]
	v_mfma_f32_32x32x16_bf16 v[20:35], v[218:221], v[230:233], v[20:35]
	v_mfma_f32_32x32x16_bf16 v[4:19], v[222:225], v[230:233], v[4:19]
	v_readlane_b32 s10, v253, 26
	v_readlane_b32 s11, v253, 27
	v_or_b32_e32 v68, s7, v114
	v_mov_b32_e32 v88, s10
	v_mov_b32_e32 v89, s31
	v_mov_b32_e32 v90, s29
	v_mov_b32_e32 v91, s30
	v_add_u32_e32 v84, s6, v113
	v_min_i32_e32 v69, 0x8000, v84
	s_mov_b32 s6, 0x8000
	v_ashrrev_i32_e32 v69, 12, v69
	v_cmp_gt_i32_e32 vcc, s6, v84
	v_readlane_b32 s6, v253, 28
	v_mul_hi_i32_i24_e32 v71, 0x6000, v69
	v_mul_i32_i24_e32 v70, 0x6000, v69
	v_add_u32_e32 v69, 0xffff8000, v84
	v_ashrrev_i32_e32 v72, 31, v84
	v_readlane_b32 s7, v253, 29
	v_cndmask_b32_e32 v73, 0, v72, vcc
	v_cndmask_b32_e32 v72, v69, v84, vcc
	v_mov_b32_e32 v85, s7
	v_mov_b32_e32 v86, s11
	v_mov_b32_e32 v87, s6
	v_mov_b32_e32 v92, s28
	v_ashrrev_i32_e32 v69, 31, v68
	v_lshl_add_u64 v[70:71], s[0:1], 0, v[70:71]
	v_cndmask_b32_e32 v75, v85, v86, vcc
	v_cndmask_b32_e32 v74, v87, v88, vcc
	v_lshlrev_b64 v[72:73], 12, v[72:73]
	v_cndmask_b32_e32 v77, v89, v90, vcc
	v_cndmask_b32_e32 v76, v91, v92, vcc
	v_lshlrev_b64 v[68:69], 2, v[68:69]
	v_lshl_add_u64 v[74:75], v[74:75], 0, v[72:73]
	v_lshl_add_u64 v[72:73], v[76:77], 0, v[72:73]
	v_lshl_add_u64 v[78:79], v[70:71], 0, v[68:69]
	v_lshl_add_u64 v[80:81], v[74:75], 0, v[68:69]
	v_lshl_add_u64 v[82:83], v[72:73], 0, v[68:69]
	s_movk_i32 s6, 0x7fe0
	v_cmp_gt_i32_e32 vcc, s6, v84
	v_readlane_b32 s6, v252, 40
	s_add_i32 s8, s8, s6
	s_cmpk_gt_i32 s8, 0x7ff
	v_readlane_b32 s7, v252, 41
	v_or_b32_e32 v76, 32, v84
	v_cndmask_b32_e32 v75, v89, v90, vcc
	v_cndmask_b32_e32 v74, v91, v92, vcc
	v_ashrrev_i32_e32 v70, 31, v76
	v_add_u32_e32 v72, 0xffff8020, v84
	v_cndmask_b32_e32 v71, 0, v70, vcc
	v_cndmask_b32_e32 v70, v72, v76, vcc
	v_cndmask_b32_e32 v73, v85, v86, vcc
	v_cndmask_b32_e32 v72, v87, v88, vcc
	v_lshlrev_b64 v[70:71], 12, v[70:71]
	v_lshl_add_u64 v[72:73], v[72:73], 0, v[70:71]
	v_lshl_add_u64 v[70:71], v[74:75], 0, v[70:71]
	v_lshl_add_u64 v[96:97], v[72:73], 0, v[68:69]
	v_lshl_add_u64 v[98:99], v[70:71], 0, v[68:69]
	global_load_dwordx4 v[118:121], v[78:79], off
	global_load_dwordx4 v[150:153], v[80:81], off
	global_load_dwordx4 v[122:125], v[78:79], off offset:16
	global_load_dwordx4 v[154:157], v[80:81], off offset:16
	global_load_dwordx4 v[126:129], v[78:79], off offset:64
	global_load_dwordx4 v[158:161], v[80:81], off offset:64
	global_load_dwordx4 v[130:133], v[78:79], off offset:80
	global_load_dwordx4 v[162:165], v[80:81], off offset:80
	global_load_dwordx4 v[134:137], v[78:79], off offset:128
	global_load_dwordx4 v[168:171], v[80:81], off offset:128
	global_load_dwordx4 v[138:141], v[78:79], off offset:144
	global_load_dwordx4 v[172:175], v[80:81], off offset:144
	global_load_dwordx4 v[142:145], v[78:79], off offset:192
	global_load_dwordx4 v[176:179], v[80:81], off offset:192
	global_load_dwordx4 v[146:149], v[78:79], off offset:208
	global_load_dwordx4 v[180:183], v[80:81], off offset:208
	global_load_dwordx4 v[184:187], v[96:97], off
	global_load_dwordx4 v[188:191], v[96:97], off offset:16
	global_load_dwordx4 v[192:195], v[96:97], off offset:64
	global_load_dwordx4 v[198:201], v[96:97], off offset:80
	global_load_dwordx4 v[218:221], v[96:97], off offset:128
	global_load_dwordx4 v[222:225], v[96:97], off offset:144
	global_load_dwordx4 v[226:229], v[96:97], off offset:192
	global_load_dwordx4 v[230:233], v[96:97], off offset:208
	s_waitcnt vmcnt(8)
;   template <int MF> DI void operator()(f32x16 (&acc)[MF][2], int mb, int nb, int l31, int h) const {
;     ...
;       for (int g4 = 0; g4 < 4; ++g4)
; #pragma unroll
;         for (int ni = 0; ni < 2; ++ni) {
;           const int col0 = nb + 16 * g4 + 8 * h + 4 * ni;
;           const float4 gt = *(const float4*)(gr + col0);
;           const float4 rv = *(const float4*)(rp + col0);
;           *(float4*)(op + col0) = make_float4(rv.x + gt.x * acc[mi][ni][4 * g4], rv.y + gt.y * acc[mi][ni][4 * g4 + 1], rv.z + gt.z * acc[mi][ni][4 * g4 + 2], rv.w + gt.w * acc[mi][ni][4 * g4 + 3]);
;         }
	s_nop 4
	v_fma_f32 v52, v52, v118, v150
	v_fma_f32 v53, v53, v119, v151
	v_fma_f32 v54, v54, v120, v152
	v_fma_f32 v55, v55, v121, v153
	global_store_dwordx4 v[82:83], v[52:55], off
	v_fma_f32 v36, v36, v122, v154
	v_fma_f32 v37, v37, v123, v155
	v_fma_f32 v38, v38, v124, v156
	v_fma_f32 v39, v39, v125, v157
	global_store_dwordx4 v[82:83], v[36:39], off offset:16
	v_fma_f32 v56, v56, v126, v158
	v_fma_f32 v57, v57, v127, v159
	v_fma_f32 v58, v58, v128, v160
	v_fma_f32 v59, v59, v129, v161
	global_store_dwordx4 v[82:83], v[56:59], off offset:64
	v_fma_f32 v40, v40, v130, v162
	v_fma_f32 v41, v41, v131, v163
	v_fma_f32 v42, v42, v132, v164
	v_fma_f32 v43, v43, v133, v165
	global_store_dwordx4 v[82:83], v[40:43], off offset:80
	v_fma_f32 v60, v60, v134, v168
	v_fma_f32 v61, v61, v135, v169
	v_fma_f32 v62, v62, v136, v170
	v_fma_f32 v63, v63, v137, v171
	global_store_dwordx4 v[82:83], v[60:63], off offset:128
	v_fma_f32 v44, v44, v138, v172
	v_fma_f32 v45, v45, v139, v173
	v_fma_f32 v46, v46, v140, v174
	v_fma_f32 v47, v47, v141, v175
	global_store_dwordx4 v[82:83], v[44:47], off offset:144
	v_fma_f32 v64, v64, v142, v176
	v_fma_f32 v65, v65, v143, v177
	v_fma_f32 v66, v66, v144, v178
	v_fma_f32 v67, v67, v145, v179
	global_store_dwordx4 v[82:83], v[64:67], off offset:192
	v_fma_f32 v48, v48, v146, v180
	v_fma_f32 v49, v49, v147, v181
	v_fma_f32 v50, v50, v148, v182
	v_fma_f32 v51, v51, v149, v183
	global_store_dwordx4 v[82:83], v[48:51], off offset:208
	s_waitcnt vmcnt(8)
	v_fma_f32 v20, v20, v118, v184
	v_fma_f32 v21, v21, v119, v185
	v_fma_f32 v22, v22, v120, v186
	v_fma_f32 v23, v23, v121, v187
	global_store_dwordx4 v[98:99], v[20:23], off
	v_fma_f32 v4, v4, v122, v188
	v_fma_f32 v5, v5, v123, v189
	v_fma_f32 v6, v6, v124, v190
	v_fma_f32 v7, v7, v125, v191
	global_store_dwordx4 v[98:99], v[4:7], off offset:16
	v_fma_f32 v24, v24, v126, v192
	v_fma_f32 v25, v25, v127, v193
	v_fma_f32 v26, v26, v128, v194
	v_fma_f32 v27, v27, v129, v195
	global_store_dwordx4 v[98:99], v[24:27], off offset:64
	v_fma_f32 v8, v8, v130, v198
	v_fma_f32 v9, v9, v131, v199
	v_fma_f32 v10, v10, v132, v200
	v_fma_f32 v11, v11, v133, v201
	global_store_dwordx4 v[98:99], v[8:11], off offset:80
	v_fma_f32 v28, v28, v134, v218
	v_fma_f32 v29, v29, v135, v219
	v_fma_f32 v30, v30, v136, v220
	v_fma_f32 v31, v31, v137, v221
	global_store_dwordx4 v[98:99], v[28:31], off offset:128
	v_fma_f32 v12, v12, v138, v222
	v_fma_f32 v13, v13, v139, v223
	v_fma_f32 v14, v14, v140, v224
	v_fma_f32 v15, v15, v141, v225
	global_store_dwordx4 v[98:99], v[12:15], off offset:144
	v_fma_f32 v32, v32, v142, v226
	v_fma_f32 v33, v33, v143, v227
	v_fma_f32 v34, v34, v144, v228
	v_fma_f32 v35, v35, v145, v229
	global_store_dwordx4 v[98:99], v[32:35], off offset:192
	v_fma_f32 v16, v16, v146, v230
	v_fma_f32 v17, v17, v147, v231
	v_fma_f32 v18, v18, v148, v232
	v_fma_f32 v19, v19, v149, v233
	global_store_dwordx4 v[98:99], v[16:19], off offset:208
	s_cbranch_scc0 .LBB0_305

; #define MFMA32(a, b, c) __builtin_amdgcn_mfma_f32_32x32x16_bf16((a), (b), (c), 0, 0, 0)
; template <int MF, int BK, class Epi>
; DI void gemm_phase_t(char* lds, const GemmDesc g, const Epi epi) {
;     ...
;     for (int kt = 0; kt < nk; ++kt) {
;       __syncthreads();
;       const u16* sA = sbase + (kt & 1) * STG;
;       const u16* sB = sA + BM * LS;
;       if (kt + 1 < nk) {
;         u16* nA = sbase + ((kt + 1) & 1) * STG;
; #pragma unroll
;         for (int j = 0; j < APT; ++j) *(u32x4*)(nA + (lr + RSTEP * j) * LS + lc * 8) = ra[j];
; #pragma unroll
;         for (int j = 0; j < BPT; ++j) *(u32x4*)(nA + BM * LS + (lr + RSTEP * j) * LS + lc * 8) = rb[j];
;         if (kt + 2 < nk) {
; #pragma unroll
;           for (int j = 0; j < APT; ++j) ra[j] = *(const u32x4*)(Ap + (size_t)j * RSTEP * g.lda + (kt + 2) * BK);
; #pragma unroll
;           for (int j = 0; j < BPT; ++j) rb[j] = *(const u32x4*)(Bp + (size_t)j * RSTEP * g.ldb + (kt + 2) * BK);
;         }
;       }
;       bf16x8 af[NKK][MF], bfr[NKK][2];
; #pragma unroll
;       for (int kk = 0; kk < NKK; ++kk) {
; #pragma unroll
;         for (int ni = 0; ni < 2; ++ni) bfr[kk][ni] = *(const bf16x8*)(sB + (wn * 64 + ni * 32 + l31) * LS + kk * 16 + h * 8);
; #pragma unroll
;         for (int mi = 0; mi < MF; ++mi) af[kk][mi] = *(const bf16x8*)(sA + (wm * (MF * 32) + mi * 32 + l31) * LS + kk * 16 + h * 8);
;       }
;       __builtin_amdgcn_sched_barrier(0);
; #pragma unroll
;       for (int kk = 0; kk < NKK; ++kk)
; #pragma unroll
;         for (int mi = 0; mi < MF; ++mi)
; #pragma unroll
;           for (int ni = 0; ni < 2; ++ni) acc[mi][ni] = MFMA32(bfr[kk][ni], af[kk][mi], acc[mi][ni]);
;     }
.Ldma_oi_loop:
	s_waitcnt vmcnt(0)
	s_waitcnt lgkmcnt(0)
	s_barrier
	v_mfma_f32_32x32x16_bf16 v[52:67], v[102:105], v[110:113], v[52:67]
	s_add_i32 m0, s3, 0x0
	s_nop 0
	global_load_lds_dwordx4 v68, s[98:99]
	s_add_i32 m0, s3, 0x1000
	s_nop 0
	global_load_lds_dwordx4 v69, s[98:99]
	s_add_i32 m0, s3, 0x2000
	s_nop 0
	global_load_lds_dwordx4 v70, s[98:99]
	s_add_i32 m0, s3, 0x3000
	s_nop 0
	global_load_lds_dwordx4 v71, s[98:99]
	s_add_i32 m0, s3, 0x4000
	s_nop 0
	global_load_lds_dwordx4 v68, s[100:101]
	s_add_i32 m0, s3, 0x5000
	s_nop 0
	global_load_lds_dwordx4 v69, s[100:101]
	s_add_i32 m0, s3, 0x6000
	s_nop 0
	global_load_lds_dwordx4 v70, s[100:101]
	s_add_i32 m0, s3, 0x7000
	s_nop 0
	global_load_lds_dwordx4 v71, s[100:101]
	s_add_u32 s98, s98, 0x80
	s_addc_u32 s99, s99, 0
	s_add_u32 s100, s100, 0x80
	s_addc_u32 s101, s101, 0
	v_mfma_f32_32x32x16_bf16 v[36:51], v[106:109], v[110:113], v[36:51]
	ds_read_b128 v[168:171], v238 offset:32768
	ds_read_b128 v[172:175], v238 offset:36864
	ds_read_b128 v[176:179], v80 offset:32768
	ds_read_b128 v[180:183], v80 offset:36864
	ds_read_b128 v[184:187], v239 offset:32768
	ds_read_b128 v[188:191], v239 offset:36864
	ds_read_b128 v[192:195], v81 offset:32768
	ds_read_b128 v[204:207], v81 offset:36864
	v_mfma_f32_32x32x16_bf16 v[20:35], v[102:105], v[114:117], v[20:35]
	ds_read_b128 v[82:85], v240 offset:32768
	ds_read_b128 v[86:89], v240 offset:36864
	ds_read_b128 v[90:93], v98 offset:32768
	ds_read_b128 v[218:221], v98 offset:36864
	ds_read_b128 v[222:225], v241 offset:32768
	ds_read_b128 v[226:229], v241 offset:36864
	ds_read_b128 v[230:233], v100 offset:32768
	ds_read_b128 v[234:237], v100 offset:36864
	v_mfma_f32_32x32x16_bf16 v[4:19], v[106:109], v[114:117], v[4:19]
	v_mfma_f32_32x32x16_bf16 v[52:67], v[118:121], v[126:129], v[52:67]
	v_mfma_f32_32x32x16_bf16 v[36:51], v[122:125], v[126:129], v[36:51]
	v_mfma_f32_32x32x16_bf16 v[20:35], v[118:121], v[130:133], v[20:35]
	v_mfma_f32_32x32x16_bf16 v[4:19], v[122:125], v[130:133], v[4:19]
	v_mfma_f32_32x32x16_bf16 v[52:67], v[134:137], v[142:145], v[52:67]
	v_mfma_f32_32x32x16_bf16 v[36:51], v[138:141], v[142:145], v[36:51]
	v_mfma_f32_32x32x16_bf16 v[20:35], v[134:137], v[146:149], v[20:35]
	v_mfma_f32_32x32x16_bf16 v[4:19], v[138:141], v[146:149], v[4:19]
	v_mfma_f32_32x32x16_bf16 v[52:67], v[150:153], v[158:161], v[52:67]
	v_mfma_f32_32x32x16_bf16 v[36:51], v[154:157], v[158:161], v[36:51]
	v_mfma_f32_32x32x16_bf16 v[20:35], v[150:153], v[162:165], v[20:35]
	v_mfma_f32_32x32x16_bf16 v[4:19], v[154:157], v[162:165], v[4:19]
	s_waitcnt vmcnt(0)
	s_waitcnt lgkmcnt(0)
	s_barrier
	v_mfma_f32_32x32x16_bf16 v[52:67], v[168:171], v[176:179], v[52:67]
	s_add_i32 m0, s3, 0x8000
	s_nop 0
	global_load_lds_dwordx4 v68, s[98:99]
	s_add_i32 m0, s3, 0x9000
	s_nop 0
	global_load_lds_dwordx4 v69, s[98:99]
	s_add_i32 m0, s3, 0xa000
	s_nop 0
	global_load_lds_dwordx4 v70, s[98:99]
	s_add_i32 m0, s3, 0xb000
	s_nop 0
	global_load_lds_dwordx4 v71, s[98:99]
	s_add_i32 m0, s3, 0xc000
	s_nop 0
	global_load_lds_dwordx4 v68, s[100:101]
	s_add_i32 m0, s3, 0xd000
	s_nop 0
	global_load_lds_dwordx4 v69, s[100:101]
	s_add_i32 m0, s3, 0xe000
	s_nop 0
	global_load_lds_dwordx4 v70, s[100:101]
	s_add_i32 m0, s3, 0xf000
	s_nop 0
	global_load_lds_dwordx4 v71, s[100:101]
	s_add_u32 s98, s98, 0x80
	s_addc_u32 s99, s99, 0
	s_add_u32 s100, s100, 0x80
	s_addc_u32 s101, s101, 0
	v_mfma_f32_32x32x16_bf16 v[36:51], v[172:175], v[176:179], v[36:51]
	ds_read_b128 v[102:105], v238
	ds_read_b128 v[106:109], v238 offset:4096
	ds_read_b128 v[110:113], v80
	ds_read_b128 v[114:117], v80 offset:4096
	ds_read_b128 v[118:121], v239
	ds_read_b128 v[122:125], v239 offset:4096
	ds_read_b128 v[126:129], v81
	ds_read_b128 v[130:133], v81 offset:4096
	v_mfma_f32_32x32x16_bf16 v[20:35], v[168:171], v[180:183], v[20:35]
	ds_read_b128 v[134:137], v240
	ds_read_b128 v[138:141], v240 offset:4096
	ds_read_b128 v[142:145], v98
	ds_read_b128 v[146:149], v98 offset:4096
	ds_read_b128 v[150:153], v241
	ds_read_b128 v[154:157], v241 offset:4096
	ds_read_b128 v[158:161], v100
	ds_read_b128 v[162:165], v100 offset:4096
	v_mfma_f32_32x32x16_bf16 v[4:19], v[172:175], v[180:183], v[4:19]
	v_mfma_f32_32x32x16_bf16 v[52:67], v[184:187], v[192:195], v[52:67]
	v_mfma_f32_32x32x16_bf16 v[36:51], v[188:191], v[192:195], v[36:51]
	v_mfma_f32_32x32x16_bf16 v[20:35], v[184:187], v[204:207], v[20:35]
	v_mfma_f32_32x32x16_bf16 v[4:19], v[188:191], v[204:207], v[4:19]
	v_mfma_f32_32x32x16_bf16 v[52:67], v[82:85], v[90:93], v[52:67]
	v_mfma_f32_32x32x16_bf16 v[36:51], v[86:89], v[90:93], v[36:51]
	v_mfma_f32_32x32x16_bf16 v[20:35], v[82:85], v[218:221], v[20:35]
	v_mfma_f32_32x32x16_bf16 v[4:19], v[86:89], v[218:221], v[4:19]
	v_mfma_f32_32x32x16_bf16 v[52:67], v[222:225], v[230:233], v[52:67]
	v_mfma_f32_32x32x16_bf16 v[36:51], v[226:229], v[230:233], v[36:51]
	v_mfma_f32_32x32x16_bf16 v[20:35], v[222:225], v[234:237], v[20:35]
	v_mfma_f32_32x32x16_bf16 v[4:19], v[226:229], v[234:237], v[4:19]
	s_add_i32 s2, s2, -1
	s_cmp_lg_u32 s2, 0
	s_cbranch_scc1 .Ldma_oi_loop
	s_waitcnt vmcnt(0)
	s_waitcnt lgkmcnt(0)
	s_barrier
; #define MFMA32(a, b, c) __builtin_amdgcn_mfma_f32_32x32x16_bf16((a), (b), (c), 0, 0, 0)
; template <int MF, int BK, class Epi>
; DI void gemm_phase_t(char* lds, const GemmDesc g, const Epi epi) {
;     ...
;       __builtin_amdgcn_sched_barrier(0);
; #pragma unroll
;       for (int kk = 0; kk < NKK; ++kk)
; #pragma unroll
;         for (int mi = 0; mi < MF; ++mi)
; #pragma unroll
;           for (int ni = 0; ni < 2; ++ni) acc[mi][ni] = MFMA32(bfr[kk][ni], af[kk][mi], acc[mi][ni]);
;     }
;     epi(acc, g.mbase + m0 + wm * (MF * 32), n0 + wn * 64, l31, h);
;   template <int MF> DI void operator()(f32x16 (&acc)[MF][2], int mb, int nb, int l31, int h) const {
;     ...
;     const int which = nb >> 9, head = ((nb >> 6) & 1) * 4 + ((nb >> 7) & 3);
; #pragma unroll
;     for (int mi = 0; mi < MF; ++mi) {
;       const int row = mb + mi * 32 + l31;
;       const bool isl = row < TL;
;       const int b = isl ? row >> 12 : (row - TL) >> 8;
;       const int t = isl ? row & 4095 : (row - TL) & 255;
;       float x[4][8];
; #pragma unroll
;       for (int g4 = 0; g4 < 4; ++g4)
; #pragma unroll
;         for (int k = 0; k < 4; ++k) { x[g4][k] = acc[mi][0][4 * g4 + k]; x[g4][4 + k] = acc[mi][1][4 * g4 + k]; }
;       if (isl) {
;         const float* sr = rope + (t >> 6) * 16 + 8 * h; const float* sc = rope + (t & 63) * 16 + 8 * h;
;         const float4 s1a = *(const float4*)(sr), s1b = *(const float4*)(sr + 4), c1a = *(const float4*)(sr + 1024), c1b = *(const float4*)(sr + 1028);
;         const float4 s2a = *(const float4*)(sc), s2b = *(const float4*)(sc + 4), c2a = *(const float4*)(sc + 1024), c2b = *(const float4*)(sc + 1028);
;         const float s1[8] = {s1a.x, s1a.y, s1a.z, s1a.w, s1b.x, s1b.y, s1b.z, s1b.w}, c1[8] = {c1a.x, c1a.y, c1a.z, c1a.w, c1b.x, c1b.y, c1b.z, c1b.w};
;         const float s2[8] = {s2a.x, s2a.y, s2a.z, s2a.w, s2b.x, s2b.y, s2b.z, s2b.w}, c2[8] = {c2a.x, c2a.y, c2a.z, c2a.w, c2b.x, c2b.y, c2b.z, c2b.w};
; #pragma unroll
;         for (int k = 0; k < 8; ++k) {
;           const float a = x[0][k], bq = x[1][k], cq = x[2][k], dq = x[3][k];
;           x[0][k] = a * c1[k] - bq * s1[k]; x[1][k] = bq * c1[k] + a * s1[k];
;           x[2][k] = cq * c2[k] - dq * s2[k]; x[3][k] = dq * c2[k] + cq * s2[k];
;         }
	v_mfma_f32_32x32x16_bf16 v[52:67], v[102:105], v[110:113], v[52:67]
	v_mfma_f32_32x32x16_bf16 v[36:51], v[106:109], v[110:113], v[36:51]
	ds_read_b128 v[168:171], v238 offset:32768
	ds_read_b128 v[172:175], v238 offset:36864
	ds_read_b128 v[176:179], v80 offset:32768
	ds_read_b128 v[180:183], v80 offset:36864
	ds_read_b128 v[184:187], v239 offset:32768
	ds_read_b128 v[188:191], v239 offset:36864
	ds_read_b128 v[192:195], v81 offset:32768
	ds_read_b128 v[204:207], v81 offset:36864
	v_mfma_f32_32x32x16_bf16 v[20:35], v[102:105], v[114:117], v[20:35]
	ds_read_b128 v[82:85], v240 offset:32768
	ds_read_b128 v[86:89], v240 offset:36864
	ds_read_b128 v[90:93], v98 offset:32768
	ds_read_b128 v[218:221], v98 offset:36864
	ds_read_b128 v[222:225], v241 offset:32768
	ds_read_b128 v[226:229], v241 offset:36864
	ds_read_b128 v[230:233], v100 offset:32768
	ds_read_b128 v[234:237], v100 offset:36864
	v_mfma_f32_32x32x16_bf16 v[4:19], v[106:109], v[114:117], v[4:19]
	v_mfma_f32_32x32x16_bf16 v[52:67], v[118:121], v[126:129], v[52:67]
	v_mfma_f32_32x32x16_bf16 v[36:51], v[122:125], v[126:129], v[36:51]
	v_mfma_f32_32x32x16_bf16 v[20:35], v[118:121], v[130:133], v[20:35]
	v_mfma_f32_32x32x16_bf16 v[4:19], v[122:125], v[130:133], v[4:19]
	v_mfma_f32_32x32x16_bf16 v[52:67], v[134:137], v[142:145], v[52:67]
	v_mfma_f32_32x32x16_bf16 v[36:51], v[138:141], v[142:145], v[36:51]
	v_mfma_f32_32x32x16_bf16 v[20:35], v[134:137], v[146:149], v[20:35]
	v_mfma_f32_32x32x16_bf16 v[4:19], v[138:141], v[146:149], v[4:19]
	v_mfma_f32_32x32x16_bf16 v[52:67], v[150:153], v[158:161], v[52:67]
	v_mfma_f32_32x32x16_bf16 v[36:51], v[154:157], v[158:161], v[36:51]
	v_mfma_f32_32x32x16_bf16 v[20:35], v[150:153], v[162:165], v[20:35]
	v_mfma_f32_32x32x16_bf16 v[4:19], v[154:157], v[162:165], v[4:19]
	s_waitcnt lgkmcnt(0)
	v_mfma_f32_32x32x16_bf16 v[52:67], v[168:171], v[176:179], v[52:67]
	v_mfma_f32_32x32x16_bf16 v[36:51], v[172:175], v[176:179], v[36:51]
	v_mfma_f32_32x32x16_bf16 v[20:35], v[168:171], v[180:183], v[20:35]
	v_mfma_f32_32x32x16_bf16 v[4:19], v[172:175], v[180:183], v[4:19]
	v_mfma_f32_32x32x16_bf16 v[52:67], v[184:187], v[192:195], v[52:67]
	v_mfma_f32_32x32x16_bf16 v[36:51], v[188:191], v[192:195], v[36:51]
	v_mfma_f32_32x32x16_bf16 v[20:35], v[184:187], v[204:207], v[20:35]
	v_mfma_f32_32x32x16_bf16 v[4:19], v[188:191], v[204:207], v[4:19]
	v_mfma_f32_32x32x16_bf16 v[52:67], v[82:85], v[90:93], v[52:67]
	v_mfma_f32_32x32x16_bf16 v[36:51], v[86:89], v[90:93], v[36:51]
	v_mfma_f32_32x32x16_bf16 v[20:35], v[82:85], v[218:221], v[20:35]
	v_mfma_f32_32x32x16_bf16 v[4:19], v[86:89], v[218:221], v[4:19]
	v_mfma_f32_32x32x16_bf16 v[52:67], v[222:225], v[230:233], v[52:67]
	v_mfma_f32_32x32x16_bf16 v[36:51], v[226:229], v[230:233], v[36:51]
	v_mfma_f32_32x32x16_bf16 v[20:35], v[222:225], v[234:237], v[20:35]
	v_mfma_f32_32x32x16_bf16 v[4:19], v[226:229], v[234:237], v[4:19]
	v_add_u32_e32 v70, s21, v95
	v_add_u32_e32 v89, s0, v96
	s_movk_i32 s0, 0x400
	v_cmp_gt_i32_e32 vcc, s0, v70
	v_or_b32_e32 v88, v89, v77
	s_and_saveexec_b64 s[0:1], vcc
	s_xor_b64 s[12:13], exec, s[0:1]
	s_cbranch_execz .LBB0_932
	s_movk_i32 s0, 0x7fff
	s_mov_b32 s2, 0x8000
	s_movk_i32 s14, 0xfdf
	v_cmp_lt_i32_e64 s[0:1], s0, v88
	v_cmp_gt_i32_e64 s[2:3], s2, v88
	v_bitop3_b32 v90, v89, s14, v77 bitop3:0xc8
	v_and_b32_e32 v82, 0xfc0, v89
	s_and_saveexec_b64 s[14:15], s[2:3]
	s_cbranch_execz .LBB0_913
	v_lshlrev_b32_e32 v2, 6, v90
	v_mov_b32_e32 v83, v3
	v_and_b32_e32 v2, 0x7c0, v2
	v_lshl_add_u64 v[68:69], v[78:79], 0, v[82:83]
	v_lshl_add_u64 v[86:87], v[78:79], 0, v[2:3]
	s_mov_b64 s[16:17], 0x1000
	v_lshl_add_u64 v[70:71], v[68:69], 0, s[16:17]
	v_lshl_add_u64 v[92:93], v[86:87], 0, s[16:17]
	s_movk_i32 s16, 0x1000
	global_load_dwordx4 v[102:105], v[68:69], off offset:16
	global_load_dwordx4 v[106:109], v[68:69], off
	v_add_co_u32_e32 v68, vcc, s16, v68
	s_nop 1
	v_addc_co_u32_e32 v69, vcc, 0, v69, vcc
	global_load_dwordx4 v[110:113], v[68:69], off
	global_load_dwordx4 v[114:117], v[70:71], off offset:16
	s_waitcnt vmcnt(2)
	v_pk_mul_f32 v[68:69], v[56:57], v[106:107]
	s_waitcnt vmcnt(1)
	v_pk_mul_f32 v[56:57], v[56:57], v[110:111]
	v_pk_fma_f32 v[84:85], v[52:53], v[110:111], v[68:69] neg_lo:[0,0,1] neg_hi:[0,0,1]
	v_pk_fma_f32 v[56:57], v[52:53], v[106:107], v[56:57]
	global_load_dwordx4 v[68:71], v[86:87], off offset:16
	global_load_dwordx4 v[118:121], v[86:87], off
	v_add_co_u32_e32 v52, vcc, s16, v86
	s_nop 1
	v_addc_co_u32_e32 v53, vcc, 0, v87, vcc
	global_load_dwordx4 v[122:125], v[52:53], off
	global_load_dwordx4 v[126:129], v[92:93], off offset:16
	s_waitcnt vmcnt(2)
	v_pk_mul_f32 v[52:53], v[64:65], v[118:119]
	s_waitcnt vmcnt(1)
	v_pk_fma_f32 v[86:87], v[60:61], v[122:123], v[52:53] neg_lo:[0,0,1] neg_hi:[0,0,1]
	v_pk_mul_f32 v[52:53], v[64:65], v[122:123]
	s_nop 0
	v_pk_fma_f32 v[64:65], v[60:61], v[118:119], v[52:53]
	v_pk_mul_f32 v[52:53], v[58:59], v[108:109]
	v_pk_mul_f32 v[58:59], v[58:59], v[112:113]
	v_pk_fma_f32 v[52:53], v[54:55], v[112:113], v[52:53] neg_lo:[0,0,1] neg_hi:[0,0,1]
	v_pk_fma_f32 v[58:59], v[54:55], v[108:109], v[58:59]
	v_pk_mul_f32 v[54:55], v[66:67], v[120:121]
	s_nop 0
	v_pk_fma_f32 v[60:61], v[62:63], v[124:125], v[54:55] neg_lo:[0,0,1] neg_hi:[0,0,1]
	v_pk_mul_f32 v[54:55], v[66:67], v[124:125]
	s_nop 0
	v_pk_fma_f32 v[66:67], v[62:63], v[120:121], v[54:55]
	v_pk_mul_f32 v[54:55], v[40:41], v[102:103]
	v_pk_mul_f32 v[40:41], v[40:41], v[114:115]
	v_pk_fma_f32 v[54:55], v[36:37], v[114:115], v[54:55] neg_lo:[0,0,1] neg_hi:[0,0,1]
	v_pk_fma_f32 v[40:41], v[36:37], v[102:103], v[40:41]
	v_pk_mul_f32 v[36:37], v[48:49], v[68:69]
	s_waitcnt vmcnt(0)
	v_pk_fma_f32 v[62:63], v[44:45], v[126:127], v[36:37] neg_lo:[0,0,1] neg_hi:[0,0,1]
	v_pk_mul_f32 v[36:37], v[48:49], v[126:127]
	s_nop 0
	v_pk_fma_f32 v[48:49], v[44:45], v[68:69], v[36:37]
	v_pk_mul_f32 v[36:37], v[42:43], v[104:105]
	v_pk_mul_f32 v[42:43], v[42:43], v[116:117]
	v_pk_fma_f32 v[36:37], v[38:39], v[116:117], v[36:37] neg_lo:[0,0,1] neg_hi:[0,0,1]
	v_pk_fma_f32 v[42:43], v[38:39], v[104:105], v[42:43]
	v_pk_mul_f32 v[38:39], v[50:51], v[70:71]
	s_nop 0
	v_pk_fma_f32 v[44:45], v[46:47], v[128:129], v[38:39] neg_lo:[0,0,1] neg_hi:[0,0,1]
	v_pk_mul_f32 v[38:39], v[50:51], v[128:129]
	s_nop 0
	v_pk_fma_f32 v[50:51], v[46:47], v[70:71], v[38:39]
	v_mov_b32_e32 v38, v36
	v_mov_b32_e32 v39, v37
	v_mov_b32_e32 v36, v54
	v_mov_b32_e32 v37, v55
	v_mov_b32_e32 v54, v52
	v_mov_b32_e32 v55, v53
	v_mov_b32_e32 v52, v84
	v_mov_b32_e32 v53, v85
	v_mov_b32_e32 v46, v44
	v_mov_b32_e32 v47, v45
	v_mov_b32_e32 v44, v62
	v_mov_b32_e32 v45, v63
	v_mov_b32_e32 v62, v60
	v_mov_b32_e32 v63, v61
	v_mov_b32_e32 v60, v86
	v_mov_b32_e32 v61, v87
